# stagger waves 4-7 by half an iteration in ffn_out gemm_tile K-loop (hi waves: MFMA(k-1) first, reads(k) last)
# speedup vs baseline: 1.0002x; 1.0002x over previous
.LBB0_716:
	s_and_b32 s33, s56, 31
	s_ashr_i32 s46, s56, 5
	s_mul_i32 s40, s33, 0x160000
	s_add_u32 s44, s57, s40
	s_addc_u32 s45, s76, 0
	s_mul_i32 s41, s46, 0xb0000
	s_mul_hi_i32 s40, s46, 0xb0000
	s_add_u32 s50, s77, s41
	s_addc_u32 s51, s80, s40
	s_mul_i32 s40, s33, 5
	s_add_i32 s40, s40, s46
	v_mov_b32_e32 v102, v156
	s_mul_hi_i32 s41, s40, 0x2e8ba2e9
	s_lshr_b32 s47, s41, 31
	s_waitcnt vmcnt(0)
	v_ashrrev_i32_e32 v4, 6, v102
	v_bfe_u32 v0, v102, 3, 3
	s_ashr_i32 s41, s41, 3
	v_lshl_or_b32 v5, v4, 3, v0
	s_add_i32 s41, s41, s47
	v_lshrrev_b32_e32 v6, 1, v5
	s_mul_i32 s41, s41, 44
	v_xor_b32_e32 v6, v6, v102
	s_sub_i32 s40, s40, s41
	v_mov_b64_e32 v[0:1], s[44:45]
	s_movk_i32 s41, 0x1600
	v_lshlrev_b32_e32 v6, 4, v6
	v_mad_i64_i32 v[2:3], s[44:45], v5, s41, v[0:1]
	v_and_b32_e32 v144, 0x70, v6
	v_add_u32_e32 v6, 64, v5
	v_lshl_add_u64 v[64:65], v[2:3], 0, v[144:145]
	v_mad_i64_i32 v[2:3], s[44:45], v6, s41, v[0:1]
	v_lshl_add_u64 v[66:67], v[2:3], 0, v[144:145]
	v_add_u32_e32 v2, 0x80, v5
	v_mad_i64_i32 v[2:3], s[44:45], v2, s41, v[0:1]
	v_lshl_add_u64 v[68:69], v[2:3], 0, v[144:145]
	v_add_u32_e32 v2, 0xc0, v5
	v_mad_i64_i32 v[0:1], s[44:45], v2, s41, v[0:1]
	v_lshl_add_u64 v[70:71], v[0:1], 0, v[144:145]
	v_mov_b64_e32 v[0:1], s[50:51]
	v_and_b32_e32 v76, 63, v102
	v_mad_i64_i32 v[2:3], s[44:45], v5, s41, v[0:1]
	v_mad_i64_i32 v[0:1], s[44:45], v6, s41, v[0:1]
	v_lshl_add_u64 v[74:75], v[0:1], 0, v[144:145]
	v_lshlrev_b32_e32 v0, 4, v76
	v_lshl_or_b32 v0, v4, 10, v0
	s_lshl_b32 s44, s40, 6
	v_add_u32_e32 v84, 0, v0
	s_ashr_i32 s45, s44, 31
	v_lshl_add_u64 v[72:73], v[2:3], 0, v[144:145]
	s_lshl_b64 s[44:45], s[44:45], 1
	v_readfirstlane_b32 s41, v84
	v_add_u32_e32 v2, 0x2000, v84
	v_lshl_add_u64 v[0:1], v[64:65], 0, s[44:45]
	s_mov_b32 m0, s41
	v_readfirstlane_b32 s41, v2
	v_add_u32_e32 v2, 0x4000, v84
	s_waitcnt vmcnt(0)
	s_barrier
	global_load_lds_dwordx4 v[0:1], off
	v_lshl_add_u64 v[0:1], v[66:67], 0, s[44:45]
	s_mov_b32 m0, s41
	v_readfirstlane_b32 s41, v2
	v_add_u32_e32 v2, 0x6000, v84
	global_load_lds_dwordx4 v[0:1], off
	v_lshl_add_u64 v[0:1], v[68:69], 0, s[44:45]
	s_mov_b32 m0, s41
	v_readfirstlane_b32 s41, v2
	v_add_u32_e32 v2, 0x8000, v84
	global_load_lds_dwordx4 v[0:1], off
	v_lshl_add_u64 v[0:1], v[70:71], 0, s[44:45]
	s_mov_b32 m0, s41
	v_readfirstlane_b32 s41, v2
	v_add_u32_e32 v2, 0xa000, v84
	global_load_lds_dwordx4 v[0:1], off
	v_lshl_add_u64 v[0:1], v[72:73], 0, s[44:45]
	s_mov_b32 m0, s41
	v_readfirstlane_b32 s41, v2
	s_cmp_lt_i32 s40, 43
	global_load_lds_dwordx4 v[0:1], off
	s_mov_b32 m0, s41
	s_cselect_b32 s41, 0, 0xffffffd4
	s_add_i32 s41, s40, s41
	s_lshl_b32 s41, s41, 6
	v_lshl_add_u64 v[0:1], v[74:75], 0, s[44:45]
	s_add_i32 s44, s41, 64
	v_add_u32_e32 v2, 0xc000, v84
	s_ashr_i32 s45, s44, 31
	s_lshl_b64 s[44:45], s[44:45], 1
	v_readfirstlane_b32 s41, v2
	v_add_u32_e32 v2, 0xe000, v84
	global_load_lds_dwordx4 v[0:1], off
	v_lshl_add_u64 v[0:1], v[64:65], 0, s[44:45]
	s_mov_b32 m0, s41
	v_readfirstlane_b32 s41, v2
	v_add_u32_e32 v2, 0x10000, v84
	global_load_lds_dwordx4 v[0:1], off
	v_lshl_add_u64 v[0:1], v[66:67], 0, s[44:45]
	s_mov_b32 m0, s41
	v_readfirstlane_b32 s41, v2
	v_add_u32_e32 v2, 0x12000, v84
	global_load_lds_dwordx4 v[0:1], off
	v_lshl_add_u64 v[0:1], v[68:69], 0, s[44:45]
	s_mov_b32 m0, s41
	v_readfirstlane_b32 s41, v2
	v_add_u32_e32 v2, 0x14000, v84
	global_load_lds_dwordx4 v[0:1], off
	v_lshl_add_u64 v[0:1], v[70:71], 0, s[44:45]
	s_mov_b32 m0, s41
	v_readfirstlane_b32 s41, v2
	v_add_u32_e32 v2, 0x16000, v84
	global_load_lds_dwordx4 v[0:1], off
	v_lshl_add_u64 v[0:1], v[72:73], 0, s[44:45]
	s_mov_b32 m0, s41
	v_readfirstlane_b32 s41, v2
	global_load_lds_dwordx4 v[0:1], off
	v_lshl_add_u64 v[0:1], v[74:75], 0, s[44:45]
	s_mov_b32 m0, s41
	v_and_b32_e32 v114, 15, v102
	global_load_lds_dwordx4 v[0:1], off
	v_and_b32_e32 v77, 1, v4
	v_bfe_u32 v79, v102, 4, 2
	v_bfe_u32 v0, v102, 1, 3
	v_ashrrev_i32_e32 v78, 7, v102
	v_lshlrev_b32_e32 v1, 7, v114
	v_xor_b32_e32 v2, v79, v0
	v_bitop3_b32 v0, v79, v0, 4 bitop3:0x36
	v_lshlrev_b32_e32 v3, 13, v77
	v_lshlrev_b32_e32 v0, 4, v0
	v_or3_b32 v3, v3, v1, s95
	v_lshl_or_b32 v1, v78, 13, v1
	v_lshlrev_b32_e32 v2, 4, v2
	v_or_b32_e32 v80, v0, v1
	v_or_b32_e32 v83, v3, v0
	v_mov_b32_e32 v0, 0
	v_or_b32_e32 v81, v3, v2
	v_or_b32_e32 v82, v2, v1
	s_mov_b32 s41, 0
	s_mov_b32 s44, 2
	v_mov_b32_e32 v1, v0
	v_mov_b32_e32 v2, v0
	v_mov_b32_e32 v3, v0
	v_mov_b32_e32 v4, v0
	v_mov_b32_e32 v5, v0
	v_mov_b32_e32 v6, v0
	v_mov_b32_e32 v7, v0
	v_mov_b32_e32 v8, v0
	v_mov_b32_e32 v9, v0
	v_mov_b32_e32 v10, v0
	v_mov_b32_e32 v11, v0
	v_mov_b32_e32 v12, v0
	v_mov_b32_e32 v13, v0
	v_mov_b32_e32 v14, v0
	v_mov_b32_e32 v15, v0
	v_mov_b32_e32 v16, v0
	v_mov_b32_e32 v17, v0
	v_mov_b32_e32 v18, v0
	v_mov_b32_e32 v19, v0
	v_mov_b32_e32 v20, v0
	v_mov_b32_e32 v21, v0
	v_mov_b32_e32 v22, v0
	v_mov_b32_e32 v23, v0
	v_mov_b32_e32 v24, v0
	v_mov_b32_e32 v25, v0
	v_mov_b32_e32 v26, v0
	v_mov_b32_e32 v27, v0
	v_mov_b32_e32 v28, v0
	v_mov_b32_e32 v29, v0
	v_mov_b32_e32 v30, v0
	v_mov_b32_e32 v31, v0
	v_mov_b32_e32 v36, v0
	v_mov_b32_e32 v37, v0
	v_mov_b32_e32 v38, v0
	v_mov_b32_e32 v39, v0
	v_mov_b32_e32 v44, v0
	v_mov_b32_e32 v45, v0
	v_mov_b32_e32 v46, v0
	v_mov_b32_e32 v47, v0
	v_mov_b32_e32 v32, v0
	v_mov_b32_e32 v33, v0
	v_mov_b32_e32 v34, v0
	v_mov_b32_e32 v35, v0
	v_mov_b32_e32 v40, v0
	v_mov_b32_e32 v41, v0
	v_mov_b32_e32 v42, v0
	v_mov_b32_e32 v43, v0
	v_mov_b32_e32 v48, v0
	v_mov_b32_e32 v49, v0
	v_mov_b32_e32 v50, v0
	v_mov_b32_e32 v51, v0
	v_mov_b32_e32 v52, v0
	v_mov_b32_e32 v53, v0
	v_mov_b32_e32 v54, v0
	v_mov_b32_e32 v55, v0
	v_mov_b32_e32 v56, v0
	v_mov_b32_e32 v57, v0
	v_mov_b32_e32 v58, v0
	v_mov_b32_e32 v59, v0
	v_mov_b32_e32 v60, v0
	v_mov_b32_e32 v61, v0
	v_mov_b32_e32 v62, v0
	v_mov_b32_e32 v63, v0
	v_readfirstlane_b32 s45, v156
	s_cmpk_ge_u32 s45, 0x100
	s_cbranch_scc1 .Lstg2_hi
.LBB0_717:
	s_waitcnt vmcnt(6)
	s_mul_i32 s45, s41, 0xc000
	s_add_i32 s47, s45, 0
	s_barrier
	v_add_u32_e32 v85, s47, v81
	v_add_u32_e32 v103, s47, v82
	ds_read_b128 v[86:89], v85 offset:0
	ds_read_b128 v[90:93], v85 offset:0x800
	ds_read_b128 v[94:97], v85 offset:0x1000
	ds_read_b128 v[98:101], v85 offset:0x1800
	ds_read_b128 v[104:107], v103 offset:0
	ds_read_b128 v[108:111], v103 offset:0x800
	ds_read_b128 v[116:119], v103 offset:0x1000
	ds_read_b128 v[120:123], v103 offset:0x1800
	v_add_u32_e32 v112, s47, v83
	v_add_u32_e32 v113, s47, v80
	ds_read_b128 v[124:127], v112 offset:0
	ds_read_b128 v[128:131], v112 offset:0x800
	ds_read_b128 v[132:135], v112 offset:0x1000
	ds_read_b128 v[136:139], v112 offset:0x1800
	ds_read_b128 v[140:143], v113 offset:0
	ds_read_b128 v[148:151], v113 offset:0x800
	ds_read_b128 v[152:155], v113 offset:0x1000
	s_waitcnt lgkmcnt(7)
	ds_read_b128 v[174:177], v113 offset:0x1800
	s_setprio 1
	v_mfma_f32_16x16x32_bf16 v[44:47], v[86:89], v[104:107], v[44:47]
	v_mfma_f32_16x16x32_bf16 v[36:39], v[90:93], v[104:107], v[36:39]
	v_mfma_f32_16x16x32_bf16 v[28:31], v[94:97], v[104:107], v[28:31]
	v_mfma_f32_16x16x32_bf16 v[24:27], v[98:101], v[104:107], v[24:27]
	v_mfma_f32_16x16x32_bf16 v[20:23], v[86:89], v[108:111], v[20:23]
	v_mfma_f32_16x16x32_bf16 v[16:19], v[90:93], v[108:111], v[16:19]
	v_mfma_f32_16x16x32_bf16 v[12:15], v[94:97], v[108:111], v[12:15]
	v_mfma_f32_16x16x32_bf16 v[8:11], v[98:101], v[108:111], v[8:11]
	v_mfma_f32_16x16x32_bf16 v[4:7], v[86:89], v[116:119], v[4:7]
	v_mfma_f32_16x16x32_bf16 v[0:3], v[90:93], v[116:119], v[0:3]
	v_mfma_f32_16x16x32_bf16 v[32:35], v[94:97], v[116:119], v[32:35]
	v_mfma_f32_16x16x32_bf16 v[40:43], v[98:101], v[116:119], v[40:43]
	v_mfma_f32_16x16x32_bf16 v[48:51], v[86:89], v[120:123], v[48:51]
	v_mfma_f32_16x16x32_bf16 v[52:55], v[90:93], v[120:123], v[52:55]
	v_mfma_f32_16x16x32_bf16 v[56:59], v[94:97], v[120:123], v[56:59]
	v_mfma_f32_16x16x32_bf16 v[60:63], v[98:101], v[120:123], v[60:63]
	s_setprio 0
	s_add_i32 s45, s45, 0xffff4000
	s_cmp_gt_i32 s41, 0
	s_cselect_b32 s45, s45, 0x18000
	v_add_u32_e32 v85, s45, v84
	s_add_i32 s45, s40, s44
	s_cmp_lt_i32 s45, 44
	s_cselect_b32 s47, 0, 0xffffffd4
	s_add_i32 s45, s45, s47
	s_lshl_b32 s50, s45, 6
	s_ashr_i32 s51, s50, 31
	s_lshl_b64 s[50:51], s[50:51], 1
	v_readfirstlane_b32 s45, v85
	v_add_u32_e32 v88, 0x2000, v85
	v_lshl_add_u64 v[86:87], v[64:65], 0, s[50:51]
	s_mov_b32 m0, s45
	v_readfirstlane_b32 s45, v88
	v_add_u32_e32 v88, 0x4000, v85
	global_load_lds_dwordx4 v[86:87], off
	v_lshl_add_u64 v[86:87], v[66:67], 0, s[50:51]
	s_mov_b32 m0, s45
	v_readfirstlane_b32 s45, v88
	v_add_u32_e32 v88, 0x6000, v85
	global_load_lds_dwordx4 v[86:87], off
	v_lshl_add_u64 v[86:87], v[68:69], 0, s[50:51]
	s_mov_b32 m0, s45
	v_readfirstlane_b32 s45, v88
	v_add_u32_e32 v88, 0x8000, v85
	global_load_lds_dwordx4 v[86:87], off
	v_lshl_add_u64 v[86:87], v[70:71], 0, s[50:51]
	s_mov_b32 m0, s45
	v_readfirstlane_b32 s45, v88
	v_add_u32_e32 v85, 0xa000, v85
	global_load_lds_dwordx4 v[86:87], off
	v_lshl_add_u64 v[86:87], v[72:73], 0, s[50:51]
	s_mov_b32 m0, s45
	v_readfirstlane_b32 s45, v85
	global_load_lds_dwordx4 v[86:87], off
	v_lshl_add_u64 v[86:87], v[74:75], 0, s[50:51]
	s_mov_b32 m0, s45
	s_nop 0
	global_load_lds_dwordx4 v[86:87], off
	s_waitcnt lgkmcnt(0)
	s_setprio 1
	v_mfma_f32_16x16x32_bf16 v[44:47], v[124:127], v[140:143], v[44:47]
	v_mfma_f32_16x16x32_bf16 v[36:39], v[128:131], v[140:143], v[36:39]
	v_mfma_f32_16x16x32_bf16 v[28:31], v[132:135], v[140:143], v[28:31]
	v_mfma_f32_16x16x32_bf16 v[24:27], v[136:139], v[140:143], v[24:27]
	v_mfma_f32_16x16x32_bf16 v[20:23], v[124:127], v[148:151], v[20:23]
	v_mfma_f32_16x16x32_bf16 v[16:19], v[128:131], v[148:151], v[16:19]
	v_mfma_f32_16x16x32_bf16 v[12:15], v[132:135], v[148:151], v[12:15]
	v_mfma_f32_16x16x32_bf16 v[8:11], v[136:139], v[148:151], v[8:11]
	v_mfma_f32_16x16x32_bf16 v[4:7], v[124:127], v[152:155], v[4:7]
	v_mfma_f32_16x16x32_bf16 v[0:3], v[128:131], v[152:155], v[0:3]
	v_mfma_f32_16x16x32_bf16 v[32:35], v[132:135], v[152:155], v[32:35]
	v_mfma_f32_16x16x32_bf16 v[40:43], v[136:139], v[152:155], v[40:43]
	v_mfma_f32_16x16x32_bf16 v[48:51], v[124:127], v[174:177], v[48:51]
	v_mfma_f32_16x16x32_bf16 v[52:55], v[128:131], v[174:177], v[52:55]
	v_mfma_f32_16x16x32_bf16 v[56:59], v[132:135], v[174:177], v[56:59]
	v_mfma_f32_16x16x32_bf16 v[60:63], v[136:139], v[174:177], v[60:63]
	s_setprio 0
	s_add_i32 s45, s41, 1
	s_cmp_lg_u32 s41, 2
	s_cselect_b32 s41, s45, 0
	s_add_i32 s44, s44, 1
	s_cmp_eq_u32 s44, 44
	s_cbranch_scc0 .LBB0_717
	s_branch .Lstg2_tail
.Lstg2_hi:
	v_mov_b32_e32 v86, 0
	v_mov_b32_e32 v87, 0
	v_mov_b32_e32 v88, 0
	v_mov_b32_e32 v89, 0
	v_mov_b32_e32 v90, 0
	v_mov_b32_e32 v91, 0
	v_mov_b32_e32 v92, 0
	v_mov_b32_e32 v93, 0
	v_mov_b32_e32 v94, 0
	v_mov_b32_e32 v95, 0
	v_mov_b32_e32 v96, 0
	v_mov_b32_e32 v97, 0
	v_mov_b32_e32 v98, 0
	v_mov_b32_e32 v99, 0
	v_mov_b32_e32 v100, 0
	v_mov_b32_e32 v101, 0
	v_mov_b32_e32 v104, 0
	v_mov_b32_e32 v105, 0
	v_mov_b32_e32 v106, 0
	v_mov_b32_e32 v107, 0
	v_mov_b32_e32 v108, 0
	v_mov_b32_e32 v109, 0
	v_mov_b32_e32 v110, 0
	v_mov_b32_e32 v111, 0
	v_mov_b32_e32 v116, 0
	v_mov_b32_e32 v117, 0
	v_mov_b32_e32 v118, 0
	v_mov_b32_e32 v119, 0
	v_mov_b32_e32 v120, 0
	v_mov_b32_e32 v121, 0
	v_mov_b32_e32 v122, 0
	v_mov_b32_e32 v123, 0
	v_mov_b32_e32 v124, 0
	v_mov_b32_e32 v125, 0
	v_mov_b32_e32 v126, 0
	v_mov_b32_e32 v127, 0
	v_mov_b32_e32 v128, 0
	v_mov_b32_e32 v129, 0
	v_mov_b32_e32 v130, 0
	v_mov_b32_e32 v131, 0
	v_mov_b32_e32 v132, 0
	v_mov_b32_e32 v133, 0
	v_mov_b32_e32 v134, 0
	v_mov_b32_e32 v135, 0
	v_mov_b32_e32 v136, 0
	v_mov_b32_e32 v137, 0
	v_mov_b32_e32 v138, 0
	v_mov_b32_e32 v139, 0
	v_mov_b32_e32 v140, 0
	v_mov_b32_e32 v141, 0
	v_mov_b32_e32 v142, 0
	v_mov_b32_e32 v143, 0
	v_mov_b32_e32 v148, 0
	v_mov_b32_e32 v149, 0
	v_mov_b32_e32 v150, 0
	v_mov_b32_e32 v151, 0
	v_mov_b32_e32 v152, 0
	v_mov_b32_e32 v153, 0
	v_mov_b32_e32 v154, 0
	v_mov_b32_e32 v155, 0
	v_mov_b32_e32 v174, 0
	v_mov_b32_e32 v175, 0
	v_mov_b32_e32 v176, 0
	v_mov_b32_e32 v177, 0
.Lstg2_hloop:
	s_waitcnt vmcnt(6)
	s_mul_i32 s45, s41, 0xc000
	s_add_i32 s47, s45, 0
	s_barrier
	s_setprio 1
	v_mfma_f32_16x16x32_bf16 v[44:47], v[86:89], v[104:107], v[44:47]
	v_mfma_f32_16x16x32_bf16 v[36:39], v[90:93], v[104:107], v[36:39]
	v_mfma_f32_16x16x32_bf16 v[28:31], v[94:97], v[104:107], v[28:31]
	v_mfma_f32_16x16x32_bf16 v[24:27], v[98:101], v[104:107], v[24:27]
	v_mfma_f32_16x16x32_bf16 v[20:23], v[86:89], v[108:111], v[20:23]
	v_mfma_f32_16x16x32_bf16 v[16:19], v[90:93], v[108:111], v[16:19]
	v_mfma_f32_16x16x32_bf16 v[12:15], v[94:97], v[108:111], v[12:15]
	v_mfma_f32_16x16x32_bf16 v[8:11], v[98:101], v[108:111], v[8:11]
	v_mfma_f32_16x16x32_bf16 v[4:7], v[86:89], v[116:119], v[4:7]
	v_mfma_f32_16x16x32_bf16 v[0:3], v[90:93], v[116:119], v[0:3]
	v_mfma_f32_16x16x32_bf16 v[32:35], v[94:97], v[116:119], v[32:35]
	v_mfma_f32_16x16x32_bf16 v[40:43], v[98:101], v[116:119], v[40:43]
	v_mfma_f32_16x16x32_bf16 v[48:51], v[86:89], v[120:123], v[48:51]
	v_mfma_f32_16x16x32_bf16 v[52:55], v[90:93], v[120:123], v[52:55]
	v_mfma_f32_16x16x32_bf16 v[56:59], v[94:97], v[120:123], v[56:59]
	v_mfma_f32_16x16x32_bf16 v[60:63], v[98:101], v[120:123], v[60:63]
	s_setprio 0
	s_add_i32 s45, s45, 0xffff4000
	s_cmp_gt_i32 s41, 0
	s_cselect_b32 s45, s45, 0x18000
	v_add_u32_e32 v85, s45, v84
	s_add_i32 s45, s40, s44
	s_cmp_lt_i32 s45, 44
	s_cselect_b32 s47, 0, 0xffffffd4
	s_add_i32 s45, s45, s47
	s_lshl_b32 s50, s45, 6
	s_ashr_i32 s51, s50, 31
	s_lshl_b64 s[50:51], s[50:51], 1
	v_readfirstlane_b32 s45, v85
	v_add_u32_e32 v88, 0x2000, v85
	v_lshl_add_u64 v[86:87], v[64:65], 0, s[50:51]
	s_mov_b32 m0, s45
	v_readfirstlane_b32 s45, v88
	v_add_u32_e32 v88, 0x4000, v85
	global_load_lds_dwordx4 v[86:87], off
	v_lshl_add_u64 v[86:87], v[66:67], 0, s[50:51]
	s_mov_b32 m0, s45
	v_readfirstlane_b32 s45, v88
	v_add_u32_e32 v88, 0x6000, v85
	global_load_lds_dwordx4 v[86:87], off
	v_lshl_add_u64 v[86:87], v[68:69], 0, s[50:51]
	s_mov_b32 m0, s45
	v_readfirstlane_b32 s45, v88
	v_add_u32_e32 v88, 0x8000, v85
	global_load_lds_dwordx4 v[86:87], off
	v_lshl_add_u64 v[86:87], v[70:71], 0, s[50:51]
	s_mov_b32 m0, s45
	v_readfirstlane_b32 s45, v88
	v_add_u32_e32 v85, 0xa000, v85
	global_load_lds_dwordx4 v[86:87], off
	v_lshl_add_u64 v[86:87], v[72:73], 0, s[50:51]
	s_mov_b32 m0, s45
	v_readfirstlane_b32 s45, v85
	global_load_lds_dwordx4 v[86:87], off
	v_lshl_add_u64 v[86:87], v[74:75], 0, s[50:51]
	s_mov_b32 m0, s45
	s_nop 0
	global_load_lds_dwordx4 v[86:87], off
	s_setprio 1
	v_mfma_f32_16x16x32_bf16 v[44:47], v[124:127], v[140:143], v[44:47]
	v_mfma_f32_16x16x32_bf16 v[36:39], v[128:131], v[140:143], v[36:39]
	v_mfma_f32_16x16x32_bf16 v[28:31], v[132:135], v[140:143], v[28:31]
	v_mfma_f32_16x16x32_bf16 v[24:27], v[136:139], v[140:143], v[24:27]
	v_mfma_f32_16x16x32_bf16 v[20:23], v[124:127], v[148:151], v[20:23]
	v_mfma_f32_16x16x32_bf16 v[16:19], v[128:131], v[148:151], v[16:19]
	v_mfma_f32_16x16x32_bf16 v[12:15], v[132:135], v[148:151], v[12:15]
	v_mfma_f32_16x16x32_bf16 v[8:11], v[136:139], v[148:151], v[8:11]
	v_mfma_f32_16x16x32_bf16 v[4:7], v[124:127], v[152:155], v[4:7]
	v_mfma_f32_16x16x32_bf16 v[0:3], v[128:131], v[152:155], v[0:3]
	v_mfma_f32_16x16x32_bf16 v[32:35], v[132:135], v[152:155], v[32:35]
	v_mfma_f32_16x16x32_bf16 v[40:43], v[136:139], v[152:155], v[40:43]
	v_mfma_f32_16x16x32_bf16 v[48:51], v[124:127], v[174:177], v[48:51]
	v_mfma_f32_16x16x32_bf16 v[52:55], v[128:131], v[174:177], v[52:55]
	v_mfma_f32_16x16x32_bf16 v[56:59], v[132:135], v[174:177], v[56:59]
	v_mfma_f32_16x16x32_bf16 v[60:63], v[136:139], v[174:177], v[60:63]
	s_setprio 0
	s_mul_i32 s47, s41, 0xc000
	v_add_u32_e32 v85, s47, v81
	v_add_u32_e32 v103, s47, v82
	ds_read_b128 v[86:89], v85 offset:0
	ds_read_b128 v[90:93], v85 offset:0x800
	ds_read_b128 v[94:97], v85 offset:0x1000
	ds_read_b128 v[98:101], v85 offset:0x1800
	ds_read_b128 v[104:107], v103 offset:0
	ds_read_b128 v[108:111], v103 offset:0x800
	ds_read_b128 v[116:119], v103 offset:0x1000
	ds_read_b128 v[120:123], v103 offset:0x1800
	v_add_u32_e32 v112, s47, v83
	v_add_u32_e32 v113, s47, v80
	ds_read_b128 v[124:127], v112 offset:0
	ds_read_b128 v[128:131], v112 offset:0x800
	ds_read_b128 v[132:135], v112 offset:0x1000
	ds_read_b128 v[136:139], v112 offset:0x1800
	ds_read_b128 v[140:143], v113 offset:0
	ds_read_b128 v[148:151], v113 offset:0x800
	ds_read_b128 v[152:155], v113 offset:0x1000
	ds_read_b128 v[174:177], v113 offset:0x1800
	s_waitcnt lgkmcnt(0)
	s_add_i32 s45, s41, 1
	s_cmp_lg_u32 s41, 2
	s_cselect_b32 s41, s45, 0
	s_add_i32 s44, s44, 1
	s_cmp_eq_u32 s44, 44
	s_cbranch_scc0 .Lstg2_hloop
	s_setprio 1
	v_mfma_f32_16x16x32_bf16 v[44:47], v[86:89], v[104:107], v[44:47]
	v_mfma_f32_16x16x32_bf16 v[36:39], v[90:93], v[104:107], v[36:39]
	v_mfma_f32_16x16x32_bf16 v[28:31], v[94:97], v[104:107], v[28:31]
	v_mfma_f32_16x16x32_bf16 v[24:27], v[98:101], v[104:107], v[24:27]
	v_mfma_f32_16x16x32_bf16 v[20:23], v[86:89], v[108:111], v[20:23]
	v_mfma_f32_16x16x32_bf16 v[16:19], v[90:93], v[108:111], v[16:19]
	v_mfma_f32_16x16x32_bf16 v[12:15], v[94:97], v[108:111], v[12:15]
	v_mfma_f32_16x16x32_bf16 v[8:11], v[98:101], v[108:111], v[8:11]
	v_mfma_f32_16x16x32_bf16 v[4:7], v[86:89], v[116:119], v[4:7]
	v_mfma_f32_16x16x32_bf16 v[0:3], v[90:93], v[116:119], v[0:3]
	v_mfma_f32_16x16x32_bf16 v[32:35], v[94:97], v[116:119], v[32:35]
	v_mfma_f32_16x16x32_bf16 v[40:43], v[98:101], v[116:119], v[40:43]
	v_mfma_f32_16x16x32_bf16 v[48:51], v[86:89], v[120:123], v[48:51]
	v_mfma_f32_16x16x32_bf16 v[52:55], v[90:93], v[120:123], v[52:55]
	v_mfma_f32_16x16x32_bf16 v[56:59], v[94:97], v[120:123], v[56:59]
	v_mfma_f32_16x16x32_bf16 v[60:63], v[98:101], v[120:123], v[60:63]
	s_setprio 0
	s_setprio 1
	v_mfma_f32_16x16x32_bf16 v[44:47], v[124:127], v[140:143], v[44:47]
	v_mfma_f32_16x16x32_bf16 v[36:39], v[128:131], v[140:143], v[36:39]
	v_mfma_f32_16x16x32_bf16 v[28:31], v[132:135], v[140:143], v[28:31]
	v_mfma_f32_16x16x32_bf16 v[24:27], v[136:139], v[140:143], v[24:27]
	v_mfma_f32_16x16x32_bf16 v[20:23], v[124:127], v[148:151], v[20:23]
	v_mfma_f32_16x16x32_bf16 v[16:19], v[128:131], v[148:151], v[16:19]
	v_mfma_f32_16x16x32_bf16 v[12:15], v[132:135], v[148:151], v[12:15]
	v_mfma_f32_16x16x32_bf16 v[8:11], v[136:139], v[148:151], v[8:11]
	v_mfma_f32_16x16x32_bf16 v[4:7], v[124:127], v[152:155], v[4:7]
	v_mfma_f32_16x16x32_bf16 v[0:3], v[128:131], v[152:155], v[0:3]
	v_mfma_f32_16x16x32_bf16 v[32:35], v[132:135], v[152:155], v[32:35]
	v_mfma_f32_16x16x32_bf16 v[40:43], v[136:139], v[152:155], v[40:43]
	v_mfma_f32_16x16x32_bf16 v[48:51], v[124:127], v[174:177], v[48:51]
	v_mfma_f32_16x16x32_bf16 v[52:55], v[128:131], v[174:177], v[52:55]
	v_mfma_f32_16x16x32_bf16 v[56:59], v[132:135], v[174:177], v[56:59]
	v_mfma_f32_16x16x32_bf16 v[60:63], v[136:139], v[174:177], v[60:63]
	s_setprio 0
.Lstg2_tail:
	v_sub_co_u32_e64 v64, s[40:41], s33, 16
	s_nop 0
	v_readfirstlane_b32 s44, v64
	s_ashr_i32 s44, s44, 2
	s_add_i32 s44, s44, 1
	s_and_b64 s[40:41], s[40:41], exec
	v_readlane_b32 s40, v255, 6
	s_cselect_b32 s94, 0, s44
	s_mul_i32 s40, s40, 5
	s_add_i32 s40, s94, s40
	s_mulk_i32 s40, 0x6000
	s_ashr_i32 s41, s40, 31
	s_waitcnt vmcnt(6)
	s_add_u32 s40, s93, s40
	v_add_u32_e32 v84, 0, v81
	s_addc_u32 s41, s90, s41
	s_barrier
	v_add_u32_e32 v100, 0, v82
	v_add_u32_e32 v103, 0, v80
	ds_read_b128 v[64:67], v84 offset:0
	ds_read_b128 v[68:71], v84 offset:0x800
	ds_read_b128 v[72:75], v84 offset:0x1000
	ds_read_b128 v[84:87], v84 offset:0x1800
	ds_read_b128 v[88:91], v100 offset:0
	ds_read_b128 v[92:95], v100 offset:0x800
	ds_read_b128 v[96:99], v100 offset:0x1000
	ds_read_b128 v[104:107], v100 offset:0x1800
	v_add_u32_e32 v101, 0, v83
	ds_read_b128 v[108:111], v101 offset:0
	ds_read_b128 v[116:119], v101 offset:0x800
	ds_read_b128 v[120:123], v101 offset:0x1000
	ds_read_b128 v[124:127], v101 offset:0x1800
	ds_read_b128 v[128:131], v103 offset:0
	ds_read_b128 v[132:135], v103 offset:0x800
	ds_read_b128 v[136:139], v103 offset:0x1000
	s_waitcnt lgkmcnt(7)
	ds_read_b128 v[140:143], v103 offset:0x1800
	s_setprio 1
	v_mfma_f32_16x16x32_bf16 v[44:47], v[64:67], v[88:91], v[44:47]
	v_mfma_f32_16x16x32_bf16 v[36:39], v[68:71], v[88:91], v[36:39]
	v_mfma_f32_16x16x32_bf16 v[28:31], v[72:75], v[88:91], v[28:31]
	v_mfma_f32_16x16x32_bf16 v[24:27], v[84:87], v[88:91], v[24:27]
	v_mfma_f32_16x16x32_bf16 v[20:23], v[64:67], v[92:95], v[20:23]
	v_mfma_f32_16x16x32_bf16 v[16:19], v[68:71], v[92:95], v[16:19]
	v_mfma_f32_16x16x32_bf16 v[12:15], v[72:75], v[92:95], v[12:15]
	v_mfma_f32_16x16x32_bf16 v[8:11], v[84:87], v[92:95], v[8:11]
	v_mfma_f32_16x16x32_bf16 v[4:7], v[64:67], v[96:99], v[4:7]
	v_mfma_f32_16x16x32_bf16 v[0:3], v[68:71], v[96:99], v[0:3]
	v_mfma_f32_16x16x32_bf16 v[32:35], v[72:75], v[96:99], v[32:35]
	v_mfma_f32_16x16x32_bf16 v[40:43], v[84:87], v[96:99], v[40:43]
	v_mfma_f32_16x16x32_bf16 v[48:51], v[64:67], v[104:107], v[48:51]
	v_mfma_f32_16x16x32_bf16 v[52:55], v[68:71], v[104:107], v[52:55]
	v_mfma_f32_16x16x32_bf16 v[56:59], v[72:75], v[104:107], v[56:59]
	v_mfma_f32_16x16x32_bf16 v[60:63], v[84:87], v[104:107], v[60:63]
	s_setprio 0
	s_waitcnt lgkmcnt(0)
	s_setprio 1
	v_mfma_f32_16x16x32_bf16 v[44:47], v[108:111], v[128:131], v[44:47]
	v_mfma_f32_16x16x32_bf16 v[36:39], v[116:119], v[128:131], v[36:39]
	v_mfma_f32_16x16x32_bf16 v[28:31], v[120:123], v[128:131], v[28:31]
	v_mfma_f32_16x16x32_bf16 v[24:27], v[124:127], v[128:131], v[24:27]
	v_mfma_f32_16x16x32_bf16 v[20:23], v[108:111], v[132:135], v[20:23]
	v_mfma_f32_16x16x32_bf16 v[16:19], v[116:119], v[132:135], v[16:19]
	v_mfma_f32_16x16x32_bf16 v[12:15], v[120:123], v[132:135], v[12:15]
	v_mfma_f32_16x16x32_bf16 v[8:11], v[124:127], v[132:135], v[8:11]
	v_mfma_f32_16x16x32_bf16 v[4:7], v[108:111], v[136:139], v[4:7]
	v_mfma_f32_16x16x32_bf16 v[0:3], v[116:119], v[136:139], v[0:3]
	v_mfma_f32_16x16x32_bf16 v[32:35], v[120:123], v[136:139], v[32:35]
	v_mfma_f32_16x16x32_bf16 v[40:43], v[124:127], v[136:139], v[40:43]
	v_mfma_f32_16x16x32_bf16 v[48:51], v[108:111], v[140:143], v[48:51]
	v_mfma_f32_16x16x32_bf16 v[52:55], v[116:119], v[140:143], v[52:55]
	v_mfma_f32_16x16x32_bf16 v[56:59], v[120:123], v[140:143], v[56:59]
	v_mfma_f32_16x16x32_bf16 v[60:63], v[124:127], v[140:143], v[60:63]
	s_setprio 0
	s_waitcnt vmcnt(0)
	s_add_i32 s44, 0, 0xc000
	v_add_u32_e32 v81, s44, v81
	v_add_u32_e32 v96, s44, v82
	s_barrier
	v_add_u32_e32 v100, s44, v83
	v_add_u32_e32 v101, s44, v80
	ds_read_b128 v[64:67], v81 offset:0
	ds_read_b128 v[68:71], v81 offset:0x800
	ds_read_b128 v[72:75], v81 offset:0x1000
	ds_read_b128 v[80:83], v81 offset:0x1800
	ds_read_b128 v[84:87], v96 offset:0
	ds_read_b128 v[88:91], v96 offset:0x800
	ds_read_b128 v[92:95], v96 offset:0x1000
	ds_read_b128 v[96:99], v96 offset:0x1800
	ds_read_b128 v[104:107], v100 offset:0
	ds_read_b128 v[108:111], v100 offset:0x800
	ds_read_b128 v[116:119], v100 offset:0x1000
	ds_read_b128 v[120:123], v100 offset:0x1800
	ds_read_b128 v[124:127], v101 offset:0
	ds_read_b128 v[128:131], v101 offset:0x800
	ds_read_b128 v[132:135], v101 offset:0x1000
	s_nop 0
	s_waitcnt lgkmcnt(7)
	ds_read_b128 v[136:139], v101 offset:0x1800
	s_setprio 1
	v_mfma_f32_16x16x32_bf16 v[44:47], v[64:67], v[84:87], v[44:47]
	v_mfma_f32_16x16x32_bf16 v[36:39], v[68:71], v[84:87], v[36:39]
	v_mfma_f32_16x16x32_bf16 v[28:31], v[72:75], v[84:87], v[28:31]
	v_mfma_f32_16x16x32_bf16 v[24:27], v[80:83], v[84:87], v[24:27]
	v_mfma_f32_16x16x32_bf16 v[20:23], v[64:67], v[88:91], v[20:23]
	v_mfma_f32_16x16x32_bf16 v[16:19], v[68:71], v[88:91], v[16:19]
	v_mfma_f32_16x16x32_bf16 v[12:15], v[72:75], v[88:91], v[12:15]
	v_mfma_f32_16x16x32_bf16 v[8:11], v[80:83], v[88:91], v[8:11]
	v_mfma_f32_16x16x32_bf16 v[4:7], v[64:67], v[92:95], v[4:7]
	v_mfma_f32_16x16x32_bf16 v[0:3], v[68:71], v[92:95], v[0:3]
	v_mfma_f32_16x16x32_bf16 v[32:35], v[72:75], v[92:95], v[32:35]
	v_mfma_f32_16x16x32_bf16 v[84:87], v[80:83], v[92:95], v[40:43]
	v_mfma_f32_16x16x32_bf16 v[72:75], v[72:75], v[96:99], v[56:59]
	v_mfma_f32_16x16x32_bf16 v[80:83], v[80:83], v[96:99], v[60:63]
	v_mfma_f32_16x16x32_bf16 v[88:91], v[64:67], v[96:99], v[48:51]
	v_mfma_f32_16x16x32_bf16 v[92:95], v[68:71], v[96:99], v[52:55]
	s_setprio 0
	s_waitcnt lgkmcnt(0)
	s_setprio 1
	v_mfma_f32_16x16x32_bf16 v[96:99], v[104:107], v[124:127], v[44:47]
	v_mfma_f32_16x16x32_bf16 v[140:143], v[108:111], v[124:127], v[36:39]
	v_mfma_f32_16x16x32_bf16 v[68:71], v[116:119], v[124:127], v[28:31]
	v_mfma_f32_16x16x32_bf16 v[64:67], v[120:123], v[124:127], v[24:27]
	v_mfma_f32_16x16x32_bf16 v[60:63], v[104:107], v[128:131], v[20:23]
	v_mfma_f32_16x16x32_bf16 v[56:59], v[108:111], v[128:131], v[16:19]
	v_mfma_f32_16x16x32_bf16 v[52:55], v[116:119], v[128:131], v[12:15]
	v_mfma_f32_16x16x32_bf16 v[48:51], v[120:123], v[128:131], v[8:11]
	v_mfma_f32_16x16x32_bf16 v[44:47], v[104:107], v[132:135], v[4:7]
	v_mfma_f32_16x16x32_bf16 v[40:43], v[108:111], v[132:135], v[0:3]
	v_mfma_f32_16x16x32_bf16 v[36:39], v[116:119], v[132:135], v[32:35]
	v_mfma_f32_16x16x32_bf16 v[32:35], v[120:123], v[132:135], v[84:87]
	v_mfma_f32_16x16x32_bf16 v[20:23], v[104:107], v[136:139], v[88:91]
	v_mfma_f32_16x16x32_bf16 v[16:19], v[108:111], v[136:139], v[92:95]
	v_mfma_f32_16x16x32_bf16 v[8:11], v[116:119], v[136:139], v[72:75]
	v_mfma_f32_16x16x32_bf16 v[0:3], v[120:123], v[136:139], v[80:83]
	s_setprio 0
	s_lshl_b32 s44, s46, 7
	v_lshlrev_b32_e32 v103, 6, v77
	v_lshlrev_b32_e32 v4, 3, v79
	v_or3_b32 v72, v4, s44, v103
	v_ashrrev_i32_e32 v73, 31, v72
	v_lshl_add_u64 v[4:5], v[72:73], 2, s[40:41]
	s_mov_b64 s[40:41], 0x5000
	v_lshl_add_u64 v[12:13], v[4:5], 0, s[40:41]
	s_movk_i32 s40, 0x5000
	v_add_co_u32_e32 v4, vcc, s40, v4
	v_lshlrev_b32_e32 v115, 6, v78
	s_nop 0
	v_addc_co_u32_e32 v5, vcc, 0, v5, vcc
	v_cmp_lt_i32_e32 vcc, v163, v164
	s_lshl_b32 s63, s33, 8
	global_load_dwordx4 v[28:31], v[4:5], off
	global_load_dwordx4 v[24:27], v[12:13], off offset:16
	s_nop 0
	global_load_dwordx4 v[4:7], v[12:13], off offset:144
	s_nop 0
	global_load_dwordx4 v[12:15], v[12:13], off offset:128
	v_cndmask_b32_e32 v74, v162, v163, vcc
	v_cmp_lt_i32_e32 vcc, v165, v164
	v_lshlrev_b32_e32 v105, 2, v74
	s_nop 0
	v_cndmask_b32_e32 v74, v162, v165, vcc
	v_lshlrev_b32_e32 v104, 2, v74
	v_lshl_add_u32 v74, v77, 8, v115
	v_or_b32_e32 v106, v74, v114
	v_add_u32_e32 v74, s63, v115
	v_or_b32_e32 v82, v74, v114
	v_cmp_gt_i32_e64 s[40:41], s64, v82
	v_ashrrev_i32_e32 v74, 31, v82
	v_cmp_gt_u32_e32 vcc, 16, v76
	v_cndmask_b32_e64 v83, 0, v74, s[40:41]
	v_lshlrev_b64 v[74:75], 11, v[82:83]
	v_lshl_add_u64 v[74:75], s[30:31], 0, v[74:75]
	v_lshl_add_u64 v[100:101], v[72:73], 1, v[74:75]
	global_load_dwordx4 v[74:77], v[100:101], off
	global_load_dwordx4 v[108:111], v[100:101], off offset:64
	v_lshl_add_u32 v106, v106, 3, 0
	s_waitcnt vmcnt(0)
	v_lshlrev_b32_e32 v78, 16, v74
	v_and_b32_e32 v79, 0xffff0000, v74
	v_lshlrev_b32_e32 v74, 16, v75
	v_and_b32_e32 v75, 0xffff0000, v75
	v_pk_mul_f32 v[74:75], v[74:75], s[96:97] op_sel_hi:[1,0]
	v_pk_mul_f32 v[78:79], v[78:79], s[96:97] op_sel_hi:[1,0]
	v_pk_fma_f32 v[80:81], v[98:99], v[30:31], v[74:75]
	v_lshlrev_b32_e32 v74, 16, v76
	v_and_b32_e32 v75, 0xffff0000, v76
	v_lshlrev_b32_e32 v76, 16, v77
	v_and_b32_e32 v77, 0xffff0000, v77
	v_pk_mul_f32 v[76:77], v[76:77], s[96:97] op_sel_hi:[1,0]
	v_pk_mul_f32 v[74:75], v[74:75], s[96:97] op_sel_hi:[1,0]
	v_pk_fma_f32 v[76:77], v[142:143], v[26:27], v[76:77]
	v_pk_fma_f32 v[78:79], v[96:97], v[28:29], v[78:79]
	v_mul_f32_e32 v89, v80, v80
	v_pk_fma_f32 v[74:75], v[140:141], v[24:25], v[74:75]
	v_mul_f32_e32 v88, v76, v76
	v_lshlrev_b32_e32 v98, 16, v108
	v_and_b32_e32 v99, 0xffff0000, v108
	v_lshlrev_b32_e32 v100, 16, v109
	v_and_b32_e32 v101, 0xffff0000, v109
	v_add_f32_e32 v84, v78, v79
	v_add_f32_e32 v86, v80, v81
	v_mul_f32_e32 v93, v78, v78
	v_mul_f32_e32 v95, v79, v79
	v_mul_f32_e32 v91, v81, v81
	v_mul_f32_e32 v85, v74, v74
	v_mul_f32_e32 v87, v75, v75
	v_pk_fma_f32 v[96:97], v[76:77], v[76:77], v[88:89] op_sel_hi:[1,1,0]
	v_pk_mul_f32 v[98:99], v[98:99], s[96:97] op_sel_hi:[1,0]
	v_pk_mul_f32 v[100:101], v[100:101], s[96:97] op_sel_hi:[1,0]
	v_mov_b32_e32 v92, v74
	v_mov_b32_e32 v94, v75
	v_mov_b32_e32 v88, v76
	v_mov_b32_e32 v90, v77
	v_pk_fma_f32 v[70:71], v[70:71], v[14:15], v[100:101]
	v_pk_fma_f32 v[68:69], v[68:69], v[12:13], v[98:99]
	v_lshlrev_b32_e32 v116, 16, v110
	v_and_b32_e32 v117, 0xffff0000, v110
	v_lshlrev_b32_e32 v110, 16, v111
	v_and_b32_e32 v111, 0xffff0000, v111
	v_pk_add_f32 v[92:93], v[92:93], v[94:95]
	v_pk_add_f32 v[88:89], v[88:89], v[90:91]
	v_pk_add_f32 v[84:85], v[84:85], v[86:87]
	v_mov_b32_e32 v96, v145
	v_mul_f32_e32 v109, v68, v68
	v_mul_f32_e32 v113, v69, v69
	v_mul_f32_e32 v99, v70, v70
	v_mul_f32_e32 v101, v71, v71
	v_pk_mul_f32 v[116:117], v[116:117], s[96:97] op_sel_hi:[1,0]
	v_pk_mul_f32 v[110:111], v[110:111], s[96:97] op_sel_hi:[1,0]
	v_pk_add_f32 v[88:89], v[92:93], v[88:89]
	v_pk_add_f32 v[84:85], v[84:85], v[96:97]
	v_mov_b32_e32 v108, v68
	v_mov_b32_e32 v112, v69
	v_mov_b32_e32 v98, v70
	v_mov_b32_e32 v100, v71
	v_pk_fma_f32 v[66:67], v[66:67], v[6:7], v[110:111]
	v_pk_fma_f32 v[64:65], v[64:65], v[4:5], v[116:117]
	v_pk_add_f32 v[84:85], v[88:89], v[84:85]
	v_pk_add_f32 v[86:87], v[108:109], v[112:113]
	v_pk_add_f32 v[88:89], v[98:99], v[100:101]
	v_mul_f32_e32 v111, v64, v64
	v_mul_f32_e32 v117, v65, v65
	v_mul_f32_e32 v119, v66, v66
	v_mul_f32_e32 v121, v67, v67
	v_pk_add_f32 v[86:87], v[86:87], v[88:89]
	v_mov_b32_e32 v110, v64
	v_mov_b32_e32 v116, v65
	v_mov_b32_e32 v118, v66
	v_mov_b32_e32 v120, v67
	v_pk_add_f32 v[84:85], v[84:85], v[86:87]
	v_pk_add_f32 v[86:87], v[110:111], v[116:117]
	v_pk_add_f32 v[88:89], v[118:119], v[120:121]
	s_nop 0
	v_pk_add_f32 v[86:87], v[86:87], v[88:89]
	s_nop 0
	v_pk_add_f32 v[84:85], v[84:85], v[86:87]
	ds_bpermute_b32 v86, v105, v84
	ds_bpermute_b32 v87, v105, v85
	s_waitcnt lgkmcnt(0)
	v_pk_add_f32 v[84:85], v[84:85], v[86:87]
	ds_bpermute_b32 v86, v104, v84
	ds_bpermute_b32 v87, v104, v85
	s_and_saveexec_b64 s[40:41], vcc
	s_cbranch_execz .LBB0_720
	v_add_u32_e32 v83, 0x24000, v106
	s_waitcnt lgkmcnt(0)
	v_pk_add_f32 v[84:85], v[84:85], v[86:87]
	ds_write_b64 v83, v[84:85]
